# phase_norm layer 1: eight bf16 row loads (compiler had serialized them load-wait x8) prefetched together one row ahead and copied in place
# baseline (speedup 1.0000x reference)
.LBB0_873:
	s_or_b64 exec, exec, s[2:3]
	v_and_b32_e32 v5, 63, v0
	v_ashrrev_i32_e32 v0, 4, v0
	v_and_b32_e32 v7, -4, v0
	v_lshlrev_b32_e32 v0, 4, v5
	v_cmp_lt_i32_e32 vcc, v43, v42
	v_lshl_add_u64 v[2:3], s[50:51], 0, v[0:1]
	v_lshlrev_b32_e32 v4, 3, v5
	v_cndmask_b32_e32 v0, v41, v43, vcc
	v_cmp_lt_i32_e32 vcc, v44, v42
	v_lshlrev_b32_e32 v49, 2, v0
	v_or_b32_e32 v8, 0x804, v4
	v_cndmask_b32_e32 v0, v41, v44, vcc
	v_cmp_lt_i32_e32 vcc, v45, v42
	v_lshlrev_b32_e32 v50, 2, v0
	v_or_b32_e32 v12, 0xa04, v4
	v_cndmask_b32_e32 v0, v41, v45, vcc
	v_cmp_lt_i32_e32 vcc, v46, v42
	v_lshlrev_b32_e32 v51, 2, v0
	v_or_b32_e32 v14, 0xc04, v4
	v_cndmask_b32_e32 v0, v41, v46, vcc
	v_cmp_lt_i32_e32 vcc, v47, v42
	v_lshlrev_b32_e32 v52, 2, v0
	v_or_b32_e32 v18, 0xe04, v4
	v_cndmask_b32_e32 v0, v41, v47, vcc
	v_cmp_lt_i32_e32 vcc, v48, v42
	v_or_b32_e32 v6, 0x800, v4
	v_or_b32_e32 v10, 0xa00, v4
	v_or_b32_e32 v16, 0xc00, v4
	v_or_b32_e32 v20, 0xe00, v4
	v_lshlrev_b32_e32 v53, 2, v0
	v_cndmask_b32_e32 v0, v41, v48, vcc
	v_readlane_b32 s52, v254, 12
	s_mov_b32 s2, 0
	v_lshlrev_b32_e32 v54, 2, v0
	v_lshl_add_u32 v55, v5, 5, 0
	v_add_u32_e32 v56, s10, v7
	v_lshlrev_b32_e32 v4, 1, v4
	v_lshlrev_b32_e32 v6, 1, v6
	v_lshlrev_b32_e32 v8, 1, v8
	v_lshlrev_b32_e32 v10, 1, v10
	v_lshlrev_b32_e32 v0, 1, v12
	v_lshlrev_b32_e32 v12, 1, v16
	v_lshlrev_b32_e32 v14, 1, v14
	v_lshlrev_b32_e32 v16, 1, v20
	v_mov_b32_e32 v17, v1
	v_lshlrev_b32_e32 v18, 1, v18
	v_mov_b32_e32 v19, v1
	v_mov_b32_e32 v5, v1
	v_mov_b32_e32 v7, v1
	v_mov_b32_e32 v9, v1
	v_mov_b32_e32 v11, v1
	v_readlane_b32 s56, v254, 16
	v_readlane_b32 s57, v254, 17
	s_waitcnt lgkmcnt(0)
	s_barrier
	v_readlane_b32 s53, v254, 13
	v_readlane_b32 s54, v254, 14
	v_readlane_b32 s55, v254, 15
	v_readlane_b32 s58, v254, 18
	v_readlane_b32 s59, v254, 19
	v_readlane_b32 s60, v254, 20
	v_readlane_b32 s61, v254, 21
	v_readlane_b32 s62, v254, 22
	v_readlane_b32 s63, v254, 23
	v_readlane_b32 s64, v254, 24
	v_readlane_b32 s65, v254, 25
	v_readlane_b32 s66, v254, 26
	v_readlane_b32 s67, v254, 27
	s_mov_b64 s[32:33], 0x1000
	s_mov_b64 s[34:35], 0x2000
	v_mov_b32_e32 v136, v56
	v_ashrrev_i32_e32 v137, 31, v56
	v_lshlrev_b64 v[136:137], 13, v[136:137]
	v_lshl_add_u64 v[250:251], v[2:3], 0, v[136:137]
	global_load_dwordx4 v[186:189], v[250:251], off
	global_load_dwordx4 v[190:193], v[250:251], off offset:1024
	global_load_dwordx4 v[194:197], v[250:251], off offset:2048
	global_load_dwordx4 v[198:201], v[250:251], off offset:3072
	v_lshl_add_u64 v[136:137], v[250:251], 0, s[32:33]
	global_load_dwordx4 v[202:205], v[136:137], off offset:3072
	global_load_dwordx4 v[206:209], v[136:137], off
	global_load_dwordx4 v[210:213], v[136:137], off offset:1024
	global_load_dwordx4 v[214:217], v[136:137], off offset:2048
	s_waitcnt vmcnt(0)
.LBB0_874:
	v_add_u32_e32 v20, s2, v56
	v_ashrrev_i32_e32 v21, 31, v20
	v_lshlrev_b64 v[36:37], 13, v[20:21]
	v_lshl_add_u64 v[24:25], v[2:3], 0, v[36:37]
	v_mov_b32_e32 v20, v186
	v_mov_b32_e32 v21, v187
	v_mov_b32_e32 v22, v188
	v_mov_b32_e32 v23, v189
	s_movk_i32 s3, 0x1000
	v_lshl_add_u64 v[36:37], s[56:57], 0, v[36:37]
	s_add_i32 s2, s2, 1
	s_cmp_eq_u32 s2, 4
	s_nop 0
	v_lshlrev_b32_e32 v101, 16, v20
	v_and_b32_e32 v100, 0xffff0000, v20
	v_lshlrev_b32_e32 v99, 16, v21
	v_and_b32_e32 v98, 0xffff0000, v21
	v_lshlrev_b32_e32 v97, 16, v22
	v_and_b32_e32 v96, 0xffff0000, v22
	v_lshlrev_b32_e32 v95, 16, v23
	v_and_b32_e32 v94, 0xffff0000, v23
	v_mov_b32_e32 v20, v190
	v_mov_b32_e32 v21, v191
	v_mov_b32_e32 v22, v192
	v_mov_b32_e32 v23, v193
	s_nop 0
	v_lshlrev_b32_e32 v93, 16, v20
	v_and_b32_e32 v92, 0xffff0000, v20
	v_lshlrev_b32_e32 v91, 16, v21
	v_and_b32_e32 v90, 0xffff0000, v21
	v_lshlrev_b32_e32 v88, 16, v22
	v_and_b32_e32 v86, 0xffff0000, v22
	v_lshlrev_b32_e32 v84, 16, v23
	v_and_b32_e32 v82, 0xffff0000, v23
	v_mov_b32_e32 v20, v194
	v_mov_b32_e32 v21, v195
	v_mov_b32_e32 v22, v196
	v_mov_b32_e32 v23, v197
	s_nop 0
	v_lshlrev_b32_e32 v81, 16, v20
	v_and_b32_e32 v80, 0xffff0000, v20
	v_lshlrev_b32_e32 v77, 16, v21
	v_and_b32_e32 v76, 0xffff0000, v21
	v_lshlrev_b32_e32 v73, 16, v22
	v_and_b32_e32 v72, 0xffff0000, v22
	v_lshlrev_b32_e32 v69, 16, v23
	v_and_b32_e32 v68, 0xffff0000, v23
	v_mov_b32_e32 v20, v198
	v_mov_b32_e32 v21, v199
	v_mov_b32_e32 v22, v200
	v_mov_b32_e32 v23, v201
	v_add_co_u32_e32 v24, vcc, s3, v24
	s_mov_b32 s3, 0x800000
	s_nop 0
	v_addc_co_u32_e32 v25, vcc, 0, v25, vcc
	v_mov_b32_e32 v102, v202
	v_mov_b32_e32 v103, v203
	v_mov_b32_e32 v104, v204
	v_mov_b32_e32 v105, v205
	s_nop 0
	v_lshlrev_b32_e32 v65, 16, v20
	v_and_b32_e32 v64, 0xffff0000, v20
	v_lshlrev_b32_e32 v63, 16, v21
	v_and_b32_e32 v61, 0xffff0000, v21
	v_lshlrev_b32_e32 v39, 16, v22
	v_and_b32_e32 v38, 0xffff0000, v22
	v_lshlrev_b32_e32 v15, 16, v23
	v_and_b32_e32 v13, 0xffff0000, v23
	v_mov_b32_e32 v20, v206
	v_mov_b32_e32 v21, v207
	v_mov_b32_e32 v22, v208
	v_mov_b32_e32 v23, v209
	s_nop 0
	v_lshlrev_b32_e32 v27, 16, v104
	s_nop 0
	v_lshlrev_b32_e32 v89, 16, v20
	v_and_b32_e32 v87, 0xffff0000, v20
	v_lshlrev_b32_e32 v85, 16, v21
	v_and_b32_e32 v83, 0xffff0000, v21
	v_lshlrev_b32_e32 v79, 16, v22
	v_and_b32_e32 v78, 0xffff0000, v22
	v_lshlrev_b32_e32 v75, 16, v23
	v_and_b32_e32 v74, 0xffff0000, v23
	v_mov_b32_e32 v20, v210
	v_mov_b32_e32 v21, v211
	v_mov_b32_e32 v22, v212
	v_mov_b32_e32 v23, v213
	s_nop 0
	v_lshlrev_b32_e32 v71, 16, v20
	v_and_b32_e32 v70, 0xffff0000, v20
	v_lshlrev_b32_e32 v67, 16, v21
	v_and_b32_e32 v66, 0xffff0000, v21
	v_mul_f32_e32 v20, v100, v100
	v_mul_f32_e32 v21, v96, v96
	v_fmac_f32_e32 v20, v101, v101
	v_fmac_f32_e32 v21, v97, v97
	v_fmac_f32_e32 v20, v99, v99
	v_fmac_f32_e32 v21, v95, v95
	v_fmac_f32_e32 v20, v98, v98
	v_fmac_f32_e32 v21, v94, v94
	v_add_f32_e32 v20, v20, v21
	v_mul_f32_e32 v21, v92, v92
	v_fmac_f32_e32 v21, v93, v93
	v_fmac_f32_e32 v21, v91, v91
	v_fmac_f32_e32 v21, v90, v90
	v_add_f32_e32 v20, v20, v21
	v_mul_f32_e32 v21, v86, v86
	v_fmac_f32_e32 v21, v88, v88
	v_fmac_f32_e32 v21, v84, v84
	v_fmac_f32_e32 v21, v82, v82
	v_add_f32_e32 v20, v20, v21
	v_mul_f32_e32 v21, v80, v80
	v_fmac_f32_e32 v21, v81, v81
	v_fmac_f32_e32 v21, v77, v77
	v_fmac_f32_e32 v21, v76, v76
	v_add_f32_e32 v20, v20, v21
	v_mul_f32_e32 v21, v72, v72
	v_fmac_f32_e32 v21, v73, v73
	v_fmac_f32_e32 v21, v69, v69
	v_fmac_f32_e32 v21, v68, v68
	v_add_f32_e32 v20, v20, v21
	v_mul_f32_e32 v21, v64, v64
	v_fmac_f32_e32 v21, v65, v65
	v_fmac_f32_e32 v21, v63, v63
	v_fmac_f32_e32 v21, v61, v61
	v_add_f32_e32 v20, v20, v21
	v_mul_f32_e32 v21, v38, v38
	v_fmac_f32_e32 v21, v39, v39
	v_fmac_f32_e32 v21, v15, v15
	v_fmac_f32_e32 v21, v13, v13
	v_add_f32_e32 v20, v20, v21
	v_mul_f32_e32 v21, v87, v87
	v_fmac_f32_e32 v21, v89, v89
	v_fmac_f32_e32 v21, v85, v85
	v_fmac_f32_e32 v21, v83, v83
	v_add_f32_e32 v20, v20, v21
	v_mul_f32_e32 v21, v78, v78
	v_fmac_f32_e32 v21, v79, v79
	v_fmac_f32_e32 v21, v75, v75
	v_fmac_f32_e32 v21, v74, v74
	v_add_f32_e32 v20, v20, v21
	v_mul_f32_e32 v21, v70, v70
	v_fmac_f32_e32 v21, v71, v71
	v_fmac_f32_e32 v21, v67, v67
	v_and_b32_e32 v60, 0xffff0000, v22
	v_fmac_f32_e32 v21, v66, v66
	v_lshlrev_b32_e32 v62, 16, v22
	v_add_f32_e32 v20, v20, v21
	v_mul_f32_e32 v21, v60, v60
	v_lshlrev_b32_e32 v59, 16, v23
	v_fmac_f32_e32 v21, v62, v62
	v_and_b32_e32 v58, 0xffff0000, v23
	v_fmac_f32_e32 v21, v59, v59
	v_fmac_f32_e32 v21, v58, v58
	v_add_f32_e32 v26, v20, v21
	v_mov_b32_e32 v20, v214
	v_mov_b32_e32 v21, v215
	v_mov_b32_e32 v22, v216
	v_mov_b32_e32 v23, v217
	s_cbranch_scc1 .Lnorm1_nopf
	v_lshl_add_u64 v[250:251], v[250:251], 0, s[34:35]
	global_load_dwordx4 v[186:189], v[250:251], off
	global_load_dwordx4 v[190:193], v[250:251], off offset:1024
	global_load_dwordx4 v[194:197], v[250:251], off offset:2048
	global_load_dwordx4 v[198:201], v[250:251], off offset:3072
	v_lshl_add_u64 v[136:137], v[250:251], 0, s[32:33]
	global_load_dwordx4 v[202:205], v[136:137], off offset:3072
	global_load_dwordx4 v[206:209], v[136:137], off
	global_load_dwordx4 v[210:213], v[136:137], off offset:1024
	global_load_dwordx4 v[214:217], v[136:137], off offset:2048
.Lnorm1_nopf:
	v_and_b32_e32 v25, 0xffff0000, v104
	v_and_b32_e32 v24, 0xffff0000, v102
	s_nop 0
	v_and_b32_e32 v33, 0xffff0000, v22
	v_and_b32_e32 v32, 0xffff0000, v20
	v_lshlrev_b32_e32 v35, 16, v22
	v_lshlrev_b32_e32 v34, 16, v20
	v_lshlrev_b32_e32 v30, 16, v21
	v_and_b32_e32 v28, 0xffff0000, v21
	v_pk_mul_f32 v[20:21], v[32:33], v[32:33]
	v_lshlrev_b32_e32 v31, 16, v23
	v_pk_fma_f32 v[20:21], v[34:35], v[34:35], v[20:21]
	v_and_b32_e32 v29, 0xffff0000, v23
	v_pk_fma_f32 v[20:21], v[30:31], v[30:31], v[20:21]
	v_lshlrev_b32_e32 v22, 16, v103
	v_pk_fma_f32 v[20:21], v[28:29], v[28:29], v[20:21]
	v_lshlrev_b32_e32 v23, 16, v105
	v_add_f32_e32 v20, v26, v20
	v_add_f32_e32 v57, v20, v21
	v_lshlrev_b32_e32 v26, 16, v102
	v_and_b32_e32 v20, 0xffff0000, v103
	v_pk_mul_f32 v[102:103], v[24:25], v[24:25]
	v_and_b32_e32 v21, 0xffff0000, v105
	v_pk_fma_f32 v[102:103], v[26:27], v[26:27], v[102:103]
	s_nop 0
	v_pk_fma_f32 v[102:103], v[22:23], v[22:23], v[102:103]
	s_nop 0
	v_pk_fma_f32 v[102:103], v[20:21], v[20:21], v[102:103]
	s_nop 0
	v_add_f32_e32 v57, v57, v102
	v_add_f32_e32 v57, v57, v103
	ds_bpermute_b32 v102, v49, v57
	s_waitcnt lgkmcnt(0)
	v_add_f32_e32 v57, v57, v102
	ds_bpermute_b32 v102, v50, v57
	s_waitcnt lgkmcnt(0)
	v_add_f32_e32 v57, v57, v102
	ds_bpermute_b32 v102, v51, v57
	s_waitcnt lgkmcnt(0)
	v_add_f32_e32 v57, v57, v102
	ds_bpermute_b32 v102, v52, v57
	s_waitcnt lgkmcnt(0)
	v_add_f32_e32 v57, v57, v102
	ds_bpermute_b32 v102, v53, v57
	s_waitcnt lgkmcnt(0)
	v_add_f32_e32 v57, v57, v102
	ds_bpermute_b32 v102, v54, v57
	s_waitcnt lgkmcnt(0)
	v_add_f32_e32 v57, v57, v102
	v_fmamk_f32 v57, v57, 0x39800000, v40
	v_cmp_gt_f32_e32 vcc, s3, v57
	v_mul_f32_e32 v102, 0x4b800000, v57
	s_nop 0
	v_cndmask_b32_e32 v57, v57, v102, vcc
	v_rsq_f32_e32 v57, v57
	s_nop 0
	v_mul_f32_e32 v102, 0x45800000, v57
	v_cndmask_b32_e32 v57, v57, v102, vcc
	ds_read_b128 v[102:105], v55
	ds_read_b128 v[106:109], v55 offset:16384
	v_mul_f32_e32 v101, v57, v101
	v_mul_f32_e32 v100, v57, v100
	v_mul_f32_e32 v99, v57, v99
	v_mul_f32_e32 v98, v57, v98
	s_waitcnt lgkmcnt(0)
	v_fma_f32 v101, v102, v101, v106
	v_fma_f32 v100, v103, v100, v107
	v_lshl_add_u64 v[106:107], v[36:37], 0, v[4:5]
	v_cvt_pk_bf16_f32 v100, v101, v100
	v_fma_f32 v99, v104, v99, v108
	v_fmac_f32_e32 v109, v105, v98
	v_cvt_pk_bf16_f32 v101, v99, v109
	global_store_dwordx2 v[106:107], v[100:101], off
	ds_read_b128 v[98:101], v55 offset:16
	ds_read_b128 v[102:105], v55 offset:16400
	v_mul_f32_e32 v97, v57, v97
	v_mul_f32_e32 v96, v57, v96
	v_mul_f32_e32 v95, v57, v95
	v_mul_f32_e32 v94, v57, v94
	s_waitcnt lgkmcnt(0)
	v_fma_f32 v97, v97, v98, v102
	v_fma_f32 v96, v96, v99, v103
	v_cvt_pk_bf16_f32 v96, v97, v96
	v_fma_f32 v95, v95, v100, v104
	v_fmac_f32_e32 v105, v94, v101
	v_cvt_pk_bf16_f32 v97, v95, v105
	global_store_dwordx2 v[106:107], v[96:97], off offset:8
	ds_read_b128 v[94:97], v55 offset:2048
	ds_read_b128 v[98:101], v55 offset:18432
	v_mul_f32_e32 v93, v57, v93
	v_mul_f32_e32 v92, v57, v92
	v_mul_f32_e32 v91, v57, v91
	v_mul_f32_e32 v90, v57, v90
	s_waitcnt lgkmcnt(0)
	v_fma_f32 v93, v93, v94, v98
	v_fma_f32 v92, v92, v95, v99
	v_cvt_pk_bf16_f32 v92, v93, v92
	v_fma_f32 v91, v91, v96, v100
	v_fmac_f32_e32 v101, v90, v97
	v_cvt_pk_bf16_f32 v93, v91, v101
	global_store_dwordx2 v[106:107], v[92:93], off offset:1024
	ds_read_b128 v[90:93], v55 offset:2064
	ds_read_b128 v[94:97], v55 offset:18448
	v_mul_f32_e32 v88, v57, v88
	v_mul_f32_e32 v86, v57, v86
	v_mul_f32_e32 v84, v57, v84
	v_mul_f32_e32 v82, v57, v82
	s_waitcnt lgkmcnt(0)
	v_fma_f32 v88, v88, v90, v94
	v_fma_f32 v86, v86, v91, v95
	v_cvt_pk_bf16_f32 v90, v88, v86
	v_fma_f32 v84, v84, v92, v96
	v_fmac_f32_e32 v97, v82, v93
	v_cvt_pk_bf16_f32 v91, v84, v97
	global_store_dwordx2 v[106:107], v[90:91], off offset:1032
	ds_read_b128 v[90:93], v55 offset:4096
	ds_read_b128 v[94:97], v55 offset:20480
	v_mul_f32_e32 v81, v57, v81
	v_mul_f32_e32 v80, v57, v80
	v_mul_f32_e32 v77, v57, v77
	v_mul_f32_e32 v76, v57, v76
	s_waitcnt lgkmcnt(0)
	v_fma_f32 v81, v81, v90, v94
	v_fma_f32 v80, v80, v91, v95
	v_cvt_pk_bf16_f32 v80, v81, v80
	v_fma_f32 v77, v77, v92, v96
	v_fmac_f32_e32 v97, v76, v93
	v_cvt_pk_bf16_f32 v81, v77, v97
	global_store_dwordx2 v[106:107], v[80:81], off offset:2048
	ds_read_b128 v[90:93], v55 offset:4112
	ds_read_b128 v[94:97], v55 offset:20496
	v_mul_f32_e32 v73, v57, v73
	v_mul_f32_e32 v72, v57, v72
	v_mul_f32_e32 v69, v57, v69
	v_mul_f32_e32 v68, v57, v68
	s_waitcnt lgkmcnt(0)
	v_fma_f32 v73, v73, v90, v94
	v_fma_f32 v72, v72, v91, v95
	v_cvt_pk_bf16_f32 v72, v73, v72
	v_fma_f32 v69, v69, v92, v96
	v_fmac_f32_e32 v97, v68, v93
	v_cvt_pk_bf16_f32 v73, v69, v97
	global_store_dwordx2 v[106:107], v[72:73], off offset:2056
	ds_read_b128 v[90:93], v55 offset:6144
	ds_read_b128 v[94:97], v55 offset:22528
	v_mul_f32_e32 v65, v57, v65
	v_mul_f32_e32 v64, v57, v64
	v_mul_f32_e32 v63, v57, v63
	v_mul_f32_e32 v61, v57, v61
	s_waitcnt lgkmcnt(0)
	v_fma_f32 v65, v65, v90, v94
	v_fma_f32 v64, v64, v91, v95
	v_cvt_pk_bf16_f32 v64, v65, v64
	v_fma_f32 v63, v63, v92, v96
	v_fmac_f32_e32 v97, v61, v93
	v_cvt_pk_bf16_f32 v65, v63, v97
	global_store_dwordx2 v[106:107], v[64:65], off offset:3072
	ds_read_b128 v[90:93], v55 offset:6160
	ds_read_b128 v[94:97], v55 offset:22544
	v_mul_f32_e32 v39, v57, v39
	v_mul_f32_e32 v38, v57, v38
	v_mul_f32_e32 v15, v57, v15
	v_mul_f32_e32 v13, v57, v13
	s_waitcnt lgkmcnt(0)
	v_fma_f32 v39, v39, v90, v94
	v_fma_f32 v38, v38, v91, v95
	v_cvt_pk_bf16_f32 v38, v39, v38
	v_fma_f32 v15, v15, v92, v96
	v_fmac_f32_e32 v97, v13, v93
	v_cvt_pk_bf16_f32 v39, v15, v97
	global_store_dwordx2 v[106:107], v[38:39], off offset:3080
	ds_read_b128 v[90:93], v55 offset:8192
	ds_read_b128 v[94:97], v55 offset:24576
	v_mul_f32_e32 v13, v57, v89
	v_mul_f32_e32 v15, v57, v87
	v_lshl_add_u64 v[64:65], v[36:37], 0, v[6:7]
	s_waitcnt lgkmcnt(0)
	v_fma_f32 v13, v13, v90, v94
	v_fma_f32 v15, v15, v91, v95
	v_cvt_pk_bf16_f32 v38, v13, v15
	v_mul_f32_e32 v13, v57, v85
	v_mul_f32_e32 v15, v57, v83
	v_fma_f32 v13, v13, v92, v96
	v_fmac_f32_e32 v97, v15, v93
	v_cvt_pk_bf16_f32 v39, v13, v97
	global_store_dwordx2 v[64:65], v[38:39], off
	ds_read_b128 v[80:83], v55 offset:8208
	ds_read_b128 v[84:87], v55 offset:24592
	v_mul_f32_e32 v13, v57, v79
	v_mul_f32_e32 v15, v57, v78
	v_lshl_add_u64 v[64:65], v[36:37], 0, v[8:9]
	s_waitcnt lgkmcnt(0)
	v_fma_f32 v13, v13, v80, v84
	v_fma_f32 v15, v15, v81, v85
	v_cvt_pk_bf16_f32 v38, v13, v15
	v_mul_f32_e32 v13, v57, v75
	v_mul_f32_e32 v15, v57, v74
	v_fma_f32 v13, v13, v82, v86
	v_fmac_f32_e32 v87, v15, v83
	v_cvt_pk_bf16_f32 v39, v13, v87
	global_store_dwordx2 v[64:65], v[38:39], off
	ds_read_b128 v[72:75], v55 offset:10240
	ds_read_b128 v[76:79], v55 offset:26624
	v_mul_f32_e32 v13, v57, v71
	v_mul_f32_e32 v15, v57, v70
	v_lshl_add_u64 v[64:65], v[36:37], 0, v[10:11]
	s_waitcnt lgkmcnt(0)
	v_fma_f32 v13, v13, v72, v76
	v_fma_f32 v15, v15, v73, v77
	v_cvt_pk_bf16_f32 v38, v13, v15
	v_mul_f32_e32 v13, v57, v67
	v_mul_f32_e32 v15, v57, v66
	v_fma_f32 v13, v13, v74, v78
	v_fmac_f32_e32 v79, v15, v75
	v_cvt_pk_bf16_f32 v39, v13, v79
	global_store_dwordx2 v[64:65], v[38:39], off
	ds_read_b128 v[64:67], v55 offset:10256
	ds_read_b128 v[68:71], v55 offset:26640
	v_mul_f32_e32 v13, v57, v62
	v_mul_f32_e32 v15, v57, v60
	s_waitcnt lgkmcnt(0)
	v_fma_f32 v13, v13, v64, v68
	v_fma_f32 v15, v15, v65, v69
	v_cvt_pk_bf16_f32 v38, v13, v15
	v_mul_f32_e32 v13, v57, v59
	v_mul_f32_e32 v15, v57, v58
	v_lshl_add_u64 v[58:59], v[36:37], 0, v[0:1]
	v_fma_f32 v13, v13, v66, v70
	v_fmac_f32_e32 v71, v15, v67
	v_cvt_pk_bf16_f32 v39, v13, v71
	global_store_dwordx2 v[58:59], v[38:39], off
	ds_read_b128 v[58:61], v55 offset:12288
	ds_read_b128 v[62:65], v55 offset:28672
	v_mul_f32_e32 v13, v57, v34
	v_mul_f32_e32 v15, v57, v32
	s_waitcnt lgkmcnt(0)
	v_fma_f32 v13, v13, v58, v62
	v_fma_f32 v15, v15, v59, v63
	v_cvt_pk_bf16_f32 v38, v13, v15
	v_mul_f32_e32 v13, v57, v30
	v_fma_f32 v13, v13, v60, v64
	v_mul_f32_e32 v15, v57, v28
	v_fmac_f32_e32 v65, v15, v61
	v_cvt_pk_bf16_f32 v39, v13, v65
	v_mov_b32_e32 v13, v1
	v_lshl_add_u64 v[58:59], v[36:37], 0, v[12:13]
	global_store_dwordx2 v[58:59], v[38:39], off
	ds_read_b128 v[58:61], v55 offset:12304
	ds_read_b128 v[62:65], v55 offset:28688
	v_mul_f32_e32 v15, v57, v33
	v_mul_f32_e32 v13, v57, v35
	s_waitcnt lgkmcnt(0)
	v_fma_f32 v15, v15, v59, v63
	v_fma_f32 v13, v13, v58, v62
	v_cvt_pk_bf16_f32 v28, v13, v15
	v_mul_f32_e32 v15, v57, v29
	v_fmac_f32_e32 v65, v15, v61
	v_mov_b32_e32 v15, v1
	v_mul_f32_e32 v13, v57, v31
	v_lshl_add_u64 v[30:31], v[36:37], 0, v[14:15]
	v_fma_f32 v13, v13, v60, v64
	v_cvt_pk_bf16_f32 v29, v13, v65
	global_store_dwordx2 v[30:31], v[28:29], off
	ds_read_b128 v[28:31], v55 offset:14336
	ds_read_b128 v[32:35], v55 offset:30720
	v_mul_f32_e32 v13, v57, v26
	v_mul_f32_e32 v15, v57, v24
	s_waitcnt lgkmcnt(0)
	v_fma_f32 v13, v13, v28, v32
	v_fma_f32 v15, v15, v29, v33
	v_cvt_pk_bf16_f32 v28, v13, v15
	v_mul_f32_e32 v13, v57, v22
	v_mul_f32_e32 v15, v57, v20
	v_fma_f32 v13, v13, v30, v34
	v_fmac_f32_e32 v35, v15, v31
	v_lshl_add_u64 v[30:31], v[36:37], 0, v[16:17]
	v_cvt_pk_bf16_f32 v29, v13, v35
	global_store_dwordx2 v[30:31], v[28:29], off
	ds_read_b128 v[28:31], v55 offset:14352
	ds_read_b128 v[32:35], v55 offset:30736
	v_mul_f32_e32 v13, v57, v27
	v_mul_f32_e32 v15, v57, v25
	s_waitcnt lgkmcnt(0)
	v_fma_f32 v13, v13, v28, v32
	v_fma_f32 v15, v15, v29, v33
	v_cvt_pk_bf16_f32 v20, v13, v15
	v_mul_f32_e32 v13, v57, v23
	v_mul_f32_e32 v15, v57, v21
	v_lshl_add_u64 v[22:23], v[36:37], 0, v[18:19]
	v_fma_f32 v13, v13, v30, v34
	v_fmac_f32_e32 v35, v15, v31
	v_cvt_pk_bf16_f32 v21, v13, v35
	global_store_dwordx2 v[22:23], v[20:21], off
	s_waitcnt vmcnt(16)
	s_cbranch_scc0 .LBB0_874
	s_add_i32 s12, s12, s94
	s_add_i32 s10, s10, s11
	s_cmpk_gt_i32 s12, 0xff
	s_cbranch_scc0 .LBB0_870
